# P6: second tile of each workgroup moved to the next column unit so its two epilogues are of different kinds
# speedup vs baseline: 1.0337x; 1.0024x over previous
.LBB0_635:
	s_add_i32 s21, s21, 1
	v_readlane_b32 s2, v255, 4
	s_mul_i32 s6, s21, s2
	s_mul_hi_u32 s7, s21, s33
	s_add_i32 s7, s7, s6
	s_mul_i32 s6, s21, s33
	s_add_u32 s60, s6, s80
	v_readlane_b32 s2, v255, 5
	s_addc_u32 s61, s7, s2
	s_cmp_eq_u32 s21, 1
	s_cbranch_scc0 .Lp6rot_skip
	s_add_i32 s60, s80, 32
	s_and_b32 s60, s60, 0xff
	s_addk_i32 s60, 0x100
	s_mov_b32 s61, 0
.Lp6rot_skip:
	v_cmp_gt_i64_e32 vcc, s[60:61], v[170:171]
	v_cmp_lt_i64_e64 s[6:7], s[60:61], v[168:169]
	s_cbranch_vccnz .LBB0_641
	s_ashr_i32 s9, s60, 31
	s_lshr_b32 s9, s9, 29
	s_add_i32 s9, s60, s9
	s_and_b32 s11, s9, -8
	s_sub_i32 s11, s60, s11
	s_cmp_gt_i32 s11, -1
	s_mov_b64 s[56:57], -1
	s_cbranch_scc0 .LBB0_638
	s_lshl_b32 s16, s11, 6
	s_mov_b64 s[56:57], 0
